# GEMM K-loops: counted vmcnt so both prefetch ring sets stay in flight; odd-half LDS stores interleaved with MFMAs
# speedup vs baseline: 1.0110x; 1.0110x over previous
; #define MFMA(a, b, c) __builtin_amdgcn_mfma_f32_32x32x16_bf16((a), (b), (c), 0, 0, 0)
; template <class Epi, class ColV>
; DI void gemm_tile(const bf16_t* __restrict__ A, int lda, const bf16_t* __restrict__ Bt, int ldb, int K, int m0, int n0, unsigned char* smem, Epi epi, ColV colv, const bf16_t* __restrict__ HYT = nullptr) {
;     ...
;     auto gload = [&](u32x4 (&r)[8], int kt) {
; #pragma unroll
;         for (int i = 0; i < 4; ++i) { int id = tid + 256 * i, row = id >> 3, kc = id & 7;
;             if (HYT && kt >= 12) r[i] = *(const u32x4*)(HYT + (size_t)((kt - 12) * 64 + (id >> 4)) * NT + m0 + (id & 15) * 8);
;             else r[i] = *(const u32x4*)(A + (size_t)(m0 + row) * lda + kt * 64 + kc * 8);
;             r[4 + i] = *(const u32x4*)(Bt + (size_t)(n0 + row) * ldb + kt * 64 + kc * 8); }
;     };
;     auto sstore = [&](const u32x4 (&r)[8], int buf, int kt) {
; #pragma unroll
;         for (int i = 0; i < 4; ++i) { int id = tid + 256 * i, row = id >> 3, kc = id & 7;
;             if (HYT && kt >= 12) { const int kk = id >> 4, rr = (id & 15) * 8; bf16_t* d = As + (buf * 128 + rr) * LS + kk; const bf16x8 v = __builtin_bit_cast(bf16x8, r[i]);
; #pragma unroll
;                 for (int e = 0; e < 8; ++e) d[e * LS] = (bf16_t)v[e]; }
;             else *(u32x4*)(As + (buf * 128 + row) * LS + kc * 8) = r[i];
;             *(u32x4*)(Bs + (buf * 128 + row) * LS + kc * 8) = r[4 + i]; }
;     };
;     auto step = [&](int kt, u32x4 (&ldset)[8], const u32x4 (&stset)[8]) {
;         const int buf = kt & 1;
;         if (kt + 2 < nk) gload(ldset, kt + 2);
;         const bf16_t* Ab = As + (buf * 128 + 64 * wr + li) * LS + 8 * lh;
;         const bf16_t* Bb = Bs + (buf * 128 + 64 * wc + li) * LS + 8 * lh;
;         bf16x8 fa[2][2], fb[2][2], ga[2][2], gb[2][2];
; #pragma unroll
;         for (int k2 = 0; k2 < 2; ++k2) { fa[k2][0] = ld8(Ab + 16 * k2); fa[k2][1] = ld8(Ab + 32 * LS + 16 * k2); fb[k2][0] = ld8(Bb + 16 * k2); fb[k2][1] = ld8(Bb + 32 * LS + 16 * k2); }
;         __builtin_amdgcn_sched_barrier(0);
; #pragma unroll
;         for (int k2 = 0; k2 < 2; ++k2) {
;             acc[0][0] = MFMA(fa[k2][0], fb[k2][0], acc[0][0]); acc[0][1] = MFMA(fa[k2][0], fb[k2][1], acc[0][1]);
;             acc[1][0] = MFMA(fa[k2][1], fb[k2][0], acc[1][0]); acc[1][1] = MFMA(fa[k2][1], fb[k2][1], acc[1][1]);
;         }
; #pragma unroll
.LBB0_40:
	s_cmp_lt_u32 s41, 62
	s_cselect_b64 s[18:19], -1, 0
	s_cmp_gt_u32 s41, 61
	s_cselect_b64 s[12:13], -1, 0
	s_and_b64 vcc, exec, s[12:13]
	v_lshl_add_u64 v[164:165], v[144:145], 0, v[2:3]
	v_lshl_add_u64 v[162:163], v[142:143], 0, v[2:3]
	v_lshl_add_u64 v[160:161], v[140:141], 0, v[2:3]
	v_lshl_add_u64 v[158:159], v[138:139], 0, v[2:3]
	v_lshl_add_u64 v[156:157], v[136:137], 0, v[2:3]
	v_lshl_add_u64 v[154:155], v[134:135], 0, v[2:3]
	v_lshl_add_u64 v[152:153], v[132:133], 0, v[2:3]
	v_lshl_add_u64 v[146:147], v[0:1], 0, v[2:3]
	s_cbranch_vccnz .LBB0_42
	v_add_co_u32_e32 v68, vcc, 0x48ca000, v164
	s_nop 1
	v_addc_co_u32_e32 v69, vcc, 0, v165, vcc
	v_add_co_u32_e32 v72, vcc, 0xe80000, v162
	global_load_dwordx4 v[68:71], v[68:69], off offset:256
	s_nop 0
	v_addc_co_u32_e32 v73, vcc, 0, v163, vcc
	v_add_co_u32_e32 v76, vcc, 0x48ca000, v160
	global_load_dwordx4 v[72:75], v[72:73], off offset:256
	s_nop 0
	v_addc_co_u32_e32 v77, vcc, 0, v161, vcc
	v_add_co_u32_e32 v80, vcc, 0xe80000, v158
	global_load_dwordx4 v[76:79], v[76:77], off offset:256
	s_nop 0
	v_addc_co_u32_e32 v81, vcc, 0, v159, vcc
	v_add_co_u32_e32 v84, vcc, 0x48ca000, v156
	global_load_dwordx4 v[80:83], v[80:81], off offset:256
	s_nop 0
	v_addc_co_u32_e32 v85, vcc, 0, v157, vcc
	v_add_co_u32_e32 v92, vcc, 0xe80000, v154
	global_load_dwordx4 v[84:87], v[84:85], off offset:256
	s_nop 0
	v_addc_co_u32_e32 v93, vcc, 0, v155, vcc
	v_add_co_u32_e32 v104, vcc, 0x48ca000, v152
	global_load_dwordx4 v[92:95], v[92:93], off offset:256
	s_nop 0
	v_addc_co_u32_e32 v105, vcc, 0, v153, vcc
	v_add_co_u32_e32 v112, vcc, 0xe80000, v146
	global_load_dwordx4 v[104:107], v[104:105], off offset:256
	s_nop 0
	v_addc_co_u32_e32 v113, vcc, 0, v147, vcc
	global_load_dwordx4 v[112:115], v[112:113], off offset:256
	ds_read_b128 v[174:177], v194
	ds_read_b128 v[178:181], v194 offset:32
	ds_read_b128 v[202:205], v194 offset:4608
	ds_read_b128 v[206:209], v194 offset:4640
	ds_read_b128 v[210:213], v195 offset:36864
	ds_read_b128 v[214:217], v195 offset:36896
	ds_read_b128 v[218:221], v195 offset:41472
	ds_read_b128 v[222:225], v195 offset:41504
	s_waitcnt lgkmcnt(3)
	v_mfma_f32_32x32x16_bf16 v[52:67], v[174:177], v[210:213], v[52:67]
	s_waitcnt lgkmcnt(1)
	v_mfma_f32_32x32x16_bf16 v[36:51], v[174:177], v[218:221], v[36:51]
	v_mfma_f32_32x32x16_bf16 v[4:19], v[202:205], v[218:221], v[4:19]
	s_waitcnt lgkmcnt(0)
	v_mfma_f32_32x32x16_bf16 v[36:51], v[178:181], v[222:225], v[36:51]
	v_mfma_f32_32x32x16_bf16 v[4:19], v[206:209], v[222:225], v[4:19]
	ds_read_b128 v[222:225], v195 offset:41568
	ds_read_b128 v[174:177], v194 offset:4672
	v_mfma_f32_32x32x16_bf16 v[20:35], v[202:205], v[210:213], v[20:35]
	ds_read_b128 v[210:213], v194 offset:4704
	ds_read_b128 v[202:205], v194 offset:64
	v_mfma_f32_32x32x16_bf16 v[52:67], v[178:181], v[214:217], v[52:67]
	ds_read_b128 v[218:221], v195 offset:36960
	ds_read_b128 v[178:181], v195 offset:41536
	v_mfma_f32_32x32x16_bf16 v[20:35], v[206:209], v[214:217], v[20:35]
	ds_read_b128 v[214:217], v195 offset:36928
	ds_read_b128 v[206:209], v194 offset:96
	s_waitcnt lgkmcnt(1)
	v_mfma_f32_32x32x16_bf16 v[52:67], v[202:205], v[214:217], v[52:67]
	s_waitcnt vmcnt(15)
	ds_write_b128 v190, v[88:91] offset:18432
	v_mfma_f32_32x32x16_bf16 v[36:51], v[202:205], v[178:181], v[36:51]
	s_waitcnt vmcnt(14)
	ds_write_b128 v190, v[96:99] offset:55296
	v_mfma_f32_32x32x16_bf16 v[20:35], v[174:177], v[214:217], v[20:35]
	s_waitcnt vmcnt(13)
	ds_write_b128 v191, v[100:103] offset:18432
	v_mfma_f32_32x32x16_bf16 v[4:19], v[174:177], v[178:181], v[4:19]
	s_waitcnt vmcnt(12)
	ds_write_b128 v191, v[108:111] offset:55296
	s_waitcnt lgkmcnt(4)
	v_mfma_f32_32x32x16_bf16 v[52:67], v[206:209], v[218:221], v[52:67]
	s_waitcnt vmcnt(11)
	ds_write_b128 v192, v[116:119] offset:18432
	v_mfma_f32_32x32x16_bf16 v[36:51], v[206:209], v[222:225], v[36:51]
	s_waitcnt vmcnt(10)
	ds_write_b128 v192, v[120:123] offset:55296
	v_mfma_f32_32x32x16_bf16 v[20:35], v[210:213], v[218:221], v[20:35]
	s_waitcnt vmcnt(9)
	ds_write_b128 v193, v[124:127] offset:18432
	v_mfma_f32_32x32x16_bf16 v[4:19], v[210:213], v[222:225], v[4:19]
	s_waitcnt vmcnt(8)
	ds_write_b128 v193, v[128:131] offset:55296
	s_waitcnt lgkmcnt(0)
	s_barrier
	v_add_co_u32_e32 v88, vcc, 0x48ca000, v164
	s_nop 1
	v_addc_co_u32_e32 v89, vcc, 0, v165, vcc
	v_add_co_u32_e32 v96, vcc, 0xe80000, v162
	global_load_dwordx4 v[88:91], v[88:89], off offset:384
	s_nop 0
	v_addc_co_u32_e32 v97, vcc, 0, v163, vcc
	v_add_co_u32_e32 v100, vcc, 0x48ca000, v160
	global_load_dwordx4 v[96:99], v[96:97], off offset:384
	s_nop 0
	v_addc_co_u32_e32 v101, vcc, 0, v161, vcc
	v_add_co_u32_e32 v108, vcc, 0xe80000, v158
	global_load_dwordx4 v[100:103], v[100:101], off offset:384
	s_nop 0
	v_addc_co_u32_e32 v109, vcc, 0, v159, vcc
	v_add_co_u32_e32 v116, vcc, 0x48ca000, v156
	global_load_dwordx4 v[108:111], v[108:109], off offset:384
	s_nop 0
	v_addc_co_u32_e32 v117, vcc, 0, v157, vcc
	v_add_co_u32_e32 v120, vcc, 0xe80000, v154
	global_load_dwordx4 v[116:119], v[116:117], off offset:384
	s_nop 0
	v_addc_co_u32_e32 v121, vcc, 0, v155, vcc
	v_add_co_u32_e32 v124, vcc, 0x48ca000, v152
	global_load_dwordx4 v[120:123], v[120:121], off offset:384
	s_nop 0
	v_addc_co_u32_e32 v125, vcc, 0, v153, vcc
	v_add_co_u32_e32 v128, vcc, 0xe80000, v146
	global_load_dwordx4 v[124:127], v[124:125], off offset:384
	s_nop 0
	v_addc_co_u32_e32 v129, vcc, 0, v147, vcc
	global_load_dwordx4 v[128:131], v[128:129], off offset:384
	ds_read_b128 v[174:177], v196
	ds_read_b128 v[178:181], v196 offset:32
	ds_read_b128 v[202:205], v196 offset:4608
	ds_read_b128 v[206:209], v196 offset:4640
	ds_read_b128 v[210:213], v197 offset:36864
	ds_read_b128 v[214:217], v197 offset:36896
	ds_read_b128 v[218:221], v197 offset:41472
	ds_read_b128 v[222:225], v197 offset:41504
	s_waitcnt lgkmcnt(3)
; template <class Epi, class ColV>
; DI void gemm_tile(const bf16_t* __restrict__ A, int lda, const bf16_t* __restrict__ Bt, int ldb, int K, int m0, int n0, unsigned char* smem, Epi epi, ColV colv, const bf16_t* __restrict__ HYT = nullptr) {
;     ...
;     auto step = [&](int kt, u32x4 (&ldset)[8], const u32x4 (&stset)[8]) {
;         const int buf = kt & 1;
;         if (kt + 2 < nk) gload(ldset, kt + 2);
;         const bf16_t* Ab = As + (buf * 128 + 64 * wr + li) * LS + 8 * lh;
;         const bf16_t* Bb = Bs + (buf * 128 + 64 * wc + li) * LS + 8 * lh;
;         bf16x8 fa[2][2], fb[2][2], ga[2][2], gb[2][2];
; #pragma unroll
;         for (int k2 = 0; k2 < 2; ++k2) { fa[k2][0] = ld8(Ab + 16 * k2); fa[k2][1] = ld8(Ab + 32 * LS + 16 * k2); fb[k2][0] = ld8(Bb + 16 * k2); fb[k2][1] = ld8(Bb + 32 * LS + 16 * k2); }
;         __builtin_amdgcn_sched_barrier(0);
; #pragma unroll
;         for (int k2 = 0; k2 < 2; ++k2) {
;             acc[0][0] = MFMA(fa[k2][0], fb[k2][0], acc[0][0]); acc[0][1] = MFMA(fa[k2][0], fb[k2][1], acc[0][1]);
;             acc[1][0] = MFMA(fa[k2][1], fb[k2][0], acc[1][0]); acc[1][1] = MFMA(fa[k2][1], fb[k2][1], acc[1][1]);
;         }
; #pragma unroll
;         for (int k2 = 0; k2 < 2; ++k2) { const int ks = 2 + k2; ga[k2][0] = ld8(Ab + 16 * ks); ga[k2][1] = ld8(Ab + 32 * LS + 16 * ks); gb[k2][0] = ld8(Bb + 16 * ks); gb[k2][1] = ld8(Bb + 32 * LS + 16 * ks); }
; #pragma unroll
;         for (int k2 = 0; k2 < 2; ++k2) {
;             acc[0][0] = MFMA(ga[k2][0], gb[k2][0], acc[0][0]); acc[0][1] = MFMA(ga[k2][0], gb[k2][1], acc[0][1]);
;             acc[1][0] = MFMA(ga[k2][1], gb[k2][0], acc[1][0]); acc[1][1] = MFMA(ga[k2][1], gb[k2][1], acc[1][1]);
;         }
;         if (kt + 1 < nk) sstore(stset, buf ^ 1, kt + 1);
; #pragma unroll
;         for (int i = 0; i < 8; ++i) { __builtin_amdgcn_sched_group_barrier(0x008, 1, 0); __builtin_amdgcn_sched_group_barrier(0x100, 1, 0); }
; #pragma unroll
;         for (int i = 0; i < 8; ++i) { __builtin_amdgcn_sched_group_barrier(0x008, 1, 0); __builtin_amdgcn_sched_group_barrier(0x200, 1, 0); }
;         __builtin_amdgcn_sched_barrier(0);
;         __syncthreads();
;     };
;     gload(R0, 0); gload(R1, 1);
;     sstore(R0, 0, 0); __syncthreads();
;     for (int kt = 0; kt < nk; kt += 2) {
;         step(kt, R0, R1);
;         if (kt + 1 < nk) step(kt + 1, R1, R0);
;     }
	v_mfma_f32_32x32x16_bf16 v[52:67], v[174:177], v[210:213], v[52:67]
	s_waitcnt lgkmcnt(1)
	v_mfma_f32_32x32x16_bf16 v[36:51], v[174:177], v[218:221], v[36:51]
	v_mfma_f32_32x32x16_bf16 v[4:19], v[202:205], v[218:221], v[4:19]
	s_waitcnt lgkmcnt(0)
	v_mfma_f32_32x32x16_bf16 v[36:51], v[178:181], v[222:225], v[36:51]
	v_mfma_f32_32x32x16_bf16 v[4:19], v[206:209], v[222:225], v[4:19]
	ds_read_b128 v[222:225], v197 offset:41568
	ds_read_b128 v[174:177], v196 offset:4672
	v_mfma_f32_32x32x16_bf16 v[20:35], v[202:205], v[210:213], v[20:35]
	ds_read_b128 v[210:213], v196 offset:4704
	ds_read_b128 v[202:205], v196 offset:64
	v_mfma_f32_32x32x16_bf16 v[52:67], v[178:181], v[214:217], v[52:67]
	ds_read_b128 v[218:221], v197 offset:36960
	ds_read_b128 v[178:181], v197 offset:41536
	v_mfma_f32_32x32x16_bf16 v[20:35], v[206:209], v[214:217], v[20:35]
	ds_read_b128 v[214:217], v197 offset:36928
	ds_read_b128 v[206:209], v196 offset:96
	s_waitcnt lgkmcnt(1)
	v_mfma_f32_32x32x16_bf16 v[52:67], v[202:205], v[214:217], v[52:67]
	s_waitcnt vmcnt(15)
	ds_write_b128 v198, v[68:71]
	v_mfma_f32_32x32x16_bf16 v[36:51], v[202:205], v[178:181], v[36:51]
	s_waitcnt vmcnt(14)
	ds_write_b128 v198, v[72:75] offset:36864
	v_mfma_f32_32x32x16_bf16 v[20:35], v[174:177], v[214:217], v[20:35]
	s_waitcnt vmcnt(13)
	ds_write_b128 v199, v[76:79]
	v_mfma_f32_32x32x16_bf16 v[4:19], v[174:177], v[178:181], v[4:19]
	s_waitcnt vmcnt(12)
	ds_write_b128 v199, v[80:83] offset:36864
	s_waitcnt lgkmcnt(4)
	v_mfma_f32_32x32x16_bf16 v[52:67], v[206:209], v[218:221], v[52:67]
	s_waitcnt vmcnt(11)
	ds_write_b128 v200, v[84:87]
	v_mfma_f32_32x32x16_bf16 v[36:51], v[206:209], v[222:225], v[36:51]
	s_waitcnt vmcnt(10)
	ds_write_b128 v200, v[92:95] offset:36864
	v_mfma_f32_32x32x16_bf16 v[20:35], v[210:213], v[218:221], v[20:35]
	s_waitcnt vmcnt(9)
	ds_write_b128 v201, v[104:107]
	v_mfma_f32_32x32x16_bf16 v[4:19], v[210:213], v[222:225], v[4:19]
	s_waitcnt vmcnt(8)
	ds_write_b128 v201, v[112:115] offset:36864
	s_branch .LBB0_39
.LBB0_42:
	ds_read_b128 v[174:177], v194
	ds_read_b128 v[178:181], v194 offset:32
	ds_read_b128 v[202:205], v194 offset:4608
	ds_read_b128 v[206:209], v194 offset:4640
	ds_read_b128 v[210:213], v195 offset:36864
	ds_read_b128 v[214:217], v195 offset:36896
	ds_read_b128 v[218:221], v195 offset:41472
	ds_read_b128 v[222:225], v195 offset:41504
	s_waitcnt lgkmcnt(3)
	v_mfma_f32_32x32x16_bf16 v[52:67], v[174:177], v[210:213], v[52:67]
	s_waitcnt lgkmcnt(1)
	v_mfma_f32_32x32x16_bf16 v[36:51], v[174:177], v[218:221], v[36:51]
	v_mfma_f32_32x32x16_bf16 v[4:19], v[202:205], v[218:221], v[4:19]
	s_waitcnt lgkmcnt(0)
	v_mfma_f32_32x32x16_bf16 v[36:51], v[178:181], v[222:225], v[36:51]
	v_mfma_f32_32x32x16_bf16 v[4:19], v[206:209], v[222:225], v[4:19]
	ds_read_b128 v[222:225], v195 offset:41568
	ds_read_b128 v[174:177], v194 offset:4672
	v_mfma_f32_32x32x16_bf16 v[20:35], v[202:205], v[210:213], v[20:35]
	ds_read_b128 v[210:213], v194 offset:4704
	ds_read_b128 v[202:205], v194 offset:64
	v_mfma_f32_32x32x16_bf16 v[52:67], v[178:181], v[214:217], v[52:67]
	ds_read_b128 v[218:221], v195 offset:36960
	ds_read_b128 v[178:181], v195 offset:41536
	v_mfma_f32_32x32x16_bf16 v[20:35], v[206:209], v[214:217], v[20:35]
	ds_read_b128 v[214:217], v195 offset:36928
	ds_read_b128 v[206:209], v194 offset:96
	s_waitcnt lgkmcnt(1)
	v_mfma_f32_32x32x16_bf16 v[52:67], v[202:205], v[214:217], v[52:67]
	s_waitcnt vmcnt(7)
	ds_write_b128 v190, v[88:91] offset:18432
	v_mfma_f32_32x32x16_bf16 v[36:51], v[202:205], v[178:181], v[36:51]
	s_waitcnt vmcnt(6)
	ds_write_b128 v190, v[96:99] offset:55296
	v_mfma_f32_32x32x16_bf16 v[20:35], v[174:177], v[214:217], v[20:35]
	s_waitcnt vmcnt(5)
	ds_write_b128 v191, v[100:103] offset:18432
	v_mfma_f32_32x32x16_bf16 v[4:19], v[174:177], v[178:181], v[4:19]
	s_waitcnt vmcnt(4)
	ds_write_b128 v191, v[108:111] offset:55296
	s_waitcnt lgkmcnt(4)
	v_mfma_f32_32x32x16_bf16 v[52:67], v[206:209], v[218:221], v[52:67]
	s_waitcnt vmcnt(3)
	ds_write_b128 v192, v[116:119] offset:18432
	v_mfma_f32_32x32x16_bf16 v[36:51], v[206:209], v[222:225], v[36:51]
	s_waitcnt vmcnt(2)
	ds_write_b128 v192, v[120:123] offset:55296
	v_mfma_f32_32x32x16_bf16 v[20:35], v[210:213], v[218:221], v[20:35]
	s_waitcnt vmcnt(1)
	ds_write_b128 v193, v[124:127] offset:18432
	v_mfma_f32_32x32x16_bf16 v[4:19], v[210:213], v[222:225], v[4:19]
	s_waitcnt vmcnt(0)
	ds_write_b128 v193, v[128:131] offset:55296
	s_waitcnt lgkmcnt(0)
	s_barrier
	ds_read_b128 v[152:155], v196
	ds_read_b128 v[156:159], v196 offset:32
	ds_read_b128 v[160:163], v196 offset:4608
	ds_read_b128 v[174:177], v196 offset:4640
	ds_read_b128 v[178:181], v197 offset:36864
	ds_read_b128 v[202:205], v197 offset:36896
	ds_read_b128 v[206:209], v197 offset:41472
	ds_read_b128 v[210:213], v197 offset:41504
	s_waitcnt lgkmcnt(3)
	v_mfma_f32_32x32x16_bf16 v[52:67], v[152:155], v[178:181], v[52:67]
	s_waitcnt lgkmcnt(1)
	v_mfma_f32_32x32x16_bf16 v[36:51], v[152:155], v[206:209], v[36:51]
	v_mfma_f32_32x32x16_bf16 v[20:35], v[160:163], v[178:181], v[20:35]
	v_mfma_f32_32x32x16_bf16 v[4:19], v[160:163], v[206:209], v[4:19]
	v_mfma_f32_32x32x16_bf16 v[52:67], v[156:159], v[202:205], v[52:67]
	s_waitcnt lgkmcnt(0)
	v_mfma_f32_32x32x16_bf16 v[36:51], v[156:159], v[210:213], v[36:51]
	v_mfma_f32_32x32x16_bf16 v[20:35], v[174:177], v[202:205], v[20:35]
	v_mfma_f32_32x32x16_bf16 v[4:19], v[174:177], v[210:213], v[4:19]
	ds_read_b128 v[152:155], v196 offset:64
	ds_read_b128 v[156:159], v197 offset:36928
	ds_read_b128 v[160:163], v196 offset:96
	ds_read_b128 v[174:177], v197 offset:36960
	ds_read_b128 v[178:181], v197 offset:41536
	ds_read_b128 v[202:205], v197 offset:41568
	s_waitcnt lgkmcnt(4)
	v_mfma_f32_32x32x16_bf16 v[52:67], v[152:155], v[156:159], v[52:67]
	s_waitcnt lgkmcnt(1)
	v_mfma_f32_32x32x16_bf16 v[36:51], v[152:155], v[178:181], v[36:51]
	ds_read_b128 v[152:155], v196 offset:4672
	ds_read_b128 v[206:209], v196 offset:4704
	s_waitcnt lgkmcnt(1)
	v_mfma_f32_32x32x16_bf16 v[20:35], v[152:155], v[156:159], v[20:35]
	v_mfma_f32_32x32x16_bf16 v[4:19], v[152:155], v[178:181], v[4:19]
	v_mfma_f32_32x32x16_bf16 v[52:67], v[160:163], v[174:177], v[52:67]
	v_mfma_f32_32x32x16_bf16 v[36:51], v[160:163], v[202:205], v[36:51]
	s_waitcnt lgkmcnt(0)
	v_mfma_f32_32x32x16_bf16 v[20:35], v[206:209], v[174:177], v[20:35]
	v_mfma_f32_32x32x16_bf16 v[4:19], v[206:209], v[202:205], v[4:19]
	s_branch .LBB0_39

; #define MFMA(a, b, c) __builtin_amdgcn_mfma_f32_32x32x16_bf16((a), (b), (c), 0, 0, 0)
; template <class Epi, class ColV>
; DI void gemm_tile(const bf16_t* __restrict__ A, int lda, const bf16_t* __restrict__ Bt, int ldb, int K, int m0, int n0, unsigned char* smem, Epi epi, ColV colv, const bf16_t* __restrict__ HYT = nullptr) {
;     ...
;     auto gload = [&](u32x4 (&r)[8], int kt) {
; #pragma unroll
;         for (int i = 0; i < 4; ++i) { int id = tid + 256 * i, row = id >> 3, kc = id & 7;
;             if (HYT && kt >= 12) r[i] = *(const u32x4*)(HYT + (size_t)((kt - 12) * 64 + (id >> 4)) * NT + m0 + (id & 15) * 8);
;             else r[i] = *(const u32x4*)(A + (size_t)(m0 + row) * lda + kt * 64 + kc * 8);
;             r[4 + i] = *(const u32x4*)(Bt + (size_t)(n0 + row) * ldb + kt * 64 + kc * 8); }
;     };
;     auto sstore = [&](const u32x4 (&r)[8], int buf, int kt) {
; #pragma unroll
;         for (int i = 0; i < 4; ++i) { int id = tid + 256 * i, row = id >> 3, kc = id & 7;
;             if (HYT && kt >= 12) { const int kk = id >> 4, rr = (id & 15) * 8; bf16_t* d = As + (buf * 128 + rr) * LS + kk; const bf16x8 v = __builtin_bit_cast(bf16x8, r[i]);
; #pragma unroll
;                 for (int e = 0; e < 8; ++e) d[e * LS] = (bf16_t)v[e]; }
;             else *(u32x4*)(As + (buf * 128 + row) * LS + kc * 8) = r[i];
;             *(u32x4*)(Bs + (buf * 128 + row) * LS + kc * 8) = r[4 + i]; }
;     };
;     auto step = [&](int kt, u32x4 (&ldset)[8], const u32x4 (&stset)[8]) {
;         const int buf = kt & 1;
;         if (kt + 2 < nk) gload(ldset, kt + 2);
;         const bf16_t* Ab = As + (buf * 128 + 64 * wr + li) * LS + 8 * lh;
;         const bf16_t* Bb = Bs + (buf * 128 + 64 * wc + li) * LS + 8 * lh;
;         bf16x8 fa[2][2], fb[2][2], ga[2][2], gb[2][2];
; #pragma unroll
;         for (int k2 = 0; k2 < 2; ++k2) { fa[k2][0] = ld8(Ab + 16 * k2); fa[k2][1] = ld8(Ab + 32 * LS + 16 * k2); fb[k2][0] = ld8(Bb + 16 * k2); fb[k2][1] = ld8(Bb + 32 * LS + 16 * k2); }
;         __builtin_amdgcn_sched_barrier(0);
; #pragma unroll
;         for (int k2 = 0; k2 < 2; ++k2) {
;             acc[0][0] = MFMA(fa[k2][0], fb[k2][0], acc[0][0]); acc[0][1] = MFMA(fa[k2][0], fb[k2][1], acc[0][1]);
;             acc[1][0] = MFMA(fa[k2][1], fb[k2][0], acc[1][0]); acc[1][1] = MFMA(fa[k2][1], fb[k2][1], acc[1][1]);
;         }
; #pragma unroll
.LBB0_56:
	s_cmp_lt_u32 s40, 14
	s_cselect_b64 s[18:19], -1, 0
	s_cmp_gt_u32 s40, 13
	s_cselect_b64 s[12:13], -1, 0
	s_and_b64 vcc, exec, s[12:13]
	v_lshl_add_u64 v[164:165], v[144:145], 0, v[2:3]
	v_lshl_add_u64 v[162:163], v[142:143], 0, v[2:3]
	v_lshl_add_u64 v[160:161], v[140:141], 0, v[2:3]
	v_lshl_add_u64 v[158:159], v[138:139], 0, v[2:3]
	v_lshl_add_u64 v[156:157], v[136:137], 0, v[2:3]
	v_lshl_add_u64 v[154:155], v[134:135], 0, v[2:3]
	v_lshl_add_u64 v[152:153], v[132:133], 0, v[2:3]
	v_lshl_add_u64 v[146:147], v[0:1], 0, v[2:3]
	s_cbranch_vccnz .LBB0_58
	v_add_co_u32_e32 v68, vcc, 0x26ca000, v164
	s_nop 1
	v_addc_co_u32_e32 v69, vcc, 0, v165, vcc
	v_add_co_u32_e32 v72, vcc, 0x680000, v162
	global_load_dwordx4 v[68:71], v[68:69], off offset:256
	s_nop 0
	v_addc_co_u32_e32 v73, vcc, 0, v163, vcc
	v_add_co_u32_e32 v76, vcc, 0x26ca000, v160
	global_load_dwordx4 v[72:75], v[72:73], off offset:256
	s_nop 0
	v_addc_co_u32_e32 v77, vcc, 0, v161, vcc
	v_add_co_u32_e32 v80, vcc, 0x680000, v158
	global_load_dwordx4 v[76:79], v[76:77], off offset:256
	s_nop 0
	v_addc_co_u32_e32 v81, vcc, 0, v159, vcc
	v_add_co_u32_e32 v84, vcc, 0x26ca000, v156
	global_load_dwordx4 v[80:83], v[80:81], off offset:256
	s_nop 0
	v_addc_co_u32_e32 v85, vcc, 0, v157, vcc
	v_add_co_u32_e32 v92, vcc, 0x680000, v154
	global_load_dwordx4 v[84:87], v[84:85], off offset:256
	s_nop 0
	v_addc_co_u32_e32 v93, vcc, 0, v155, vcc
	v_add_co_u32_e32 v104, vcc, 0x26ca000, v152
	global_load_dwordx4 v[92:95], v[92:93], off offset:256
	s_nop 0
	v_addc_co_u32_e32 v105, vcc, 0, v153, vcc
	v_add_co_u32_e32 v112, vcc, 0x680000, v146
	global_load_dwordx4 v[104:107], v[104:105], off offset:256
	s_nop 0
	v_addc_co_u32_e32 v113, vcc, 0, v147, vcc
	global_load_dwordx4 v[112:115], v[112:113], off offset:256
	ds_read_b128 v[174:177], v194
	ds_read_b128 v[178:181], v194 offset:32
	ds_read_b128 v[202:205], v194 offset:4608
	ds_read_b128 v[206:209], v194 offset:4640
	ds_read_b128 v[210:213], v195 offset:36864
	ds_read_b128 v[214:217], v195 offset:36896
	ds_read_b128 v[218:221], v195 offset:41472
	ds_read_b128 v[222:225], v195 offset:41504
	s_waitcnt lgkmcnt(3)
	v_mfma_f32_32x32x16_bf16 v[52:67], v[174:177], v[210:213], v[52:67]
	s_waitcnt lgkmcnt(1)
	v_mfma_f32_32x32x16_bf16 v[36:51], v[174:177], v[218:221], v[36:51]
	v_mfma_f32_32x32x16_bf16 v[4:19], v[202:205], v[218:221], v[4:19]
	s_waitcnt lgkmcnt(0)
	v_mfma_f32_32x32x16_bf16 v[36:51], v[178:181], v[222:225], v[36:51]
	v_mfma_f32_32x32x16_bf16 v[4:19], v[206:209], v[222:225], v[4:19]
	ds_read_b128 v[222:225], v195 offset:41568
	ds_read_b128 v[174:177], v194 offset:4672
	v_mfma_f32_32x32x16_bf16 v[20:35], v[202:205], v[210:213], v[20:35]
	ds_read_b128 v[210:213], v194 offset:4704
	ds_read_b128 v[202:205], v194 offset:64
	v_mfma_f32_32x32x16_bf16 v[52:67], v[178:181], v[214:217], v[52:67]
	ds_read_b128 v[218:221], v195 offset:36960
	ds_read_b128 v[178:181], v195 offset:41536
	v_mfma_f32_32x32x16_bf16 v[20:35], v[206:209], v[214:217], v[20:35]
	ds_read_b128 v[214:217], v195 offset:36928
	ds_read_b128 v[206:209], v194 offset:96
	s_waitcnt lgkmcnt(1)
	v_mfma_f32_32x32x16_bf16 v[52:67], v[202:205], v[214:217], v[52:67]
	s_waitcnt vmcnt(15)
	ds_write_b128 v167, v[88:91] offset:18432
	v_mfma_f32_32x32x16_bf16 v[36:51], v[202:205], v[178:181], v[36:51]
	s_waitcnt vmcnt(14)
	ds_write_b128 v167, v[96:99] offset:55296
	v_mfma_f32_32x32x16_bf16 v[20:35], v[174:177], v[214:217], v[20:35]
	s_waitcnt vmcnt(13)
	ds_write_b128 v190, v[100:103] offset:18432
	v_mfma_f32_32x32x16_bf16 v[4:19], v[174:177], v[178:181], v[4:19]
	s_waitcnt vmcnt(12)
	ds_write_b128 v190, v[108:111] offset:55296
	s_waitcnt lgkmcnt(4)
	v_mfma_f32_32x32x16_bf16 v[52:67], v[206:209], v[218:221], v[52:67]
	s_waitcnt vmcnt(11)
	ds_write_b128 v191, v[116:119] offset:18432
	v_mfma_f32_32x32x16_bf16 v[36:51], v[206:209], v[222:225], v[36:51]
	s_waitcnt vmcnt(10)
	ds_write_b128 v191, v[120:123] offset:55296
	v_mfma_f32_32x32x16_bf16 v[20:35], v[210:213], v[218:221], v[20:35]
	s_waitcnt vmcnt(9)
	ds_write_b128 v192, v[124:127] offset:18432
	v_mfma_f32_32x32x16_bf16 v[4:19], v[210:213], v[222:225], v[4:19]
	s_waitcnt vmcnt(8)
	ds_write_b128 v192, v[128:131] offset:55296
	s_waitcnt lgkmcnt(0)
	s_barrier
	v_add_co_u32_e32 v88, vcc, 0x26ca000, v164
	s_nop 1
	v_addc_co_u32_e32 v89, vcc, 0, v165, vcc
	v_add_co_u32_e32 v96, vcc, 0x680000, v162
	global_load_dwordx4 v[88:91], v[88:89], off offset:384
	s_nop 0
	v_addc_co_u32_e32 v97, vcc, 0, v163, vcc
	v_add_co_u32_e32 v100, vcc, 0x26ca000, v160
	global_load_dwordx4 v[96:99], v[96:97], off offset:384
	s_nop 0
	v_addc_co_u32_e32 v101, vcc, 0, v161, vcc
	v_add_co_u32_e32 v108, vcc, 0x680000, v158
	global_load_dwordx4 v[100:103], v[100:101], off offset:384
	s_nop 0
	v_addc_co_u32_e32 v109, vcc, 0, v159, vcc
	v_add_co_u32_e32 v116, vcc, 0x26ca000, v156
	global_load_dwordx4 v[108:111], v[108:109], off offset:384
	s_nop 0
	v_addc_co_u32_e32 v117, vcc, 0, v157, vcc
	v_add_co_u32_e32 v120, vcc, 0x680000, v154
	global_load_dwordx4 v[116:119], v[116:117], off offset:384
	s_nop 0
	v_addc_co_u32_e32 v121, vcc, 0, v155, vcc
	v_add_co_u32_e32 v124, vcc, 0x26ca000, v152
	global_load_dwordx4 v[120:123], v[120:121], off offset:384
	s_nop 0
	v_addc_co_u32_e32 v125, vcc, 0, v153, vcc
	v_add_co_u32_e32 v128, vcc, 0x680000, v146
	global_load_dwordx4 v[124:127], v[124:125], off offset:384
	s_nop 0
	v_addc_co_u32_e32 v129, vcc, 0, v147, vcc
	global_load_dwordx4 v[128:131], v[128:129], off offset:384
	ds_read_b128 v[174:177], v196
	ds_read_b128 v[178:181], v196 offset:32
	ds_read_b128 v[202:205], v196 offset:4608
	ds_read_b128 v[206:209], v196 offset:4640
	ds_read_b128 v[210:213], v197 offset:36864
	ds_read_b128 v[214:217], v197 offset:36896
	ds_read_b128 v[218:221], v197 offset:41472
	ds_read_b128 v[222:225], v197 offset:41504
	s_waitcnt lgkmcnt(3)
; template <class Epi, class ColV>
; DI void gemm_tile(const bf16_t* __restrict__ A, int lda, const bf16_t* __restrict__ Bt, int ldb, int K, int m0, int n0, unsigned char* smem, Epi epi, ColV colv, const bf16_t* __restrict__ HYT = nullptr) {
;     ...
;     auto step = [&](int kt, u32x4 (&ldset)[8], const u32x4 (&stset)[8]) {
;         const int buf = kt & 1;
;         if (kt + 2 < nk) gload(ldset, kt + 2);
;         const bf16_t* Ab = As + (buf * 128 + 64 * wr + li) * LS + 8 * lh;
;         const bf16_t* Bb = Bs + (buf * 128 + 64 * wc + li) * LS + 8 * lh;
;         bf16x8 fa[2][2], fb[2][2], ga[2][2], gb[2][2];
; #pragma unroll
;         for (int k2 = 0; k2 < 2; ++k2) { fa[k2][0] = ld8(Ab + 16 * k2); fa[k2][1] = ld8(Ab + 32 * LS + 16 * k2); fb[k2][0] = ld8(Bb + 16 * k2); fb[k2][1] = ld8(Bb + 32 * LS + 16 * k2); }
;         __builtin_amdgcn_sched_barrier(0);
; #pragma unroll
;         for (int k2 = 0; k2 < 2; ++k2) {
;             acc[0][0] = MFMA(fa[k2][0], fb[k2][0], acc[0][0]); acc[0][1] = MFMA(fa[k2][0], fb[k2][1], acc[0][1]);
;             acc[1][0] = MFMA(fa[k2][1], fb[k2][0], acc[1][0]); acc[1][1] = MFMA(fa[k2][1], fb[k2][1], acc[1][1]);
;         }
; #pragma unroll
;         for (int k2 = 0; k2 < 2; ++k2) { const int ks = 2 + k2; ga[k2][0] = ld8(Ab + 16 * ks); ga[k2][1] = ld8(Ab + 32 * LS + 16 * ks); gb[k2][0] = ld8(Bb + 16 * ks); gb[k2][1] = ld8(Bb + 32 * LS + 16 * ks); }
; #pragma unroll
;         for (int k2 = 0; k2 < 2; ++k2) {
;             acc[0][0] = MFMA(ga[k2][0], gb[k2][0], acc[0][0]); acc[0][1] = MFMA(ga[k2][0], gb[k2][1], acc[0][1]);
;             acc[1][0] = MFMA(ga[k2][1], gb[k2][0], acc[1][0]); acc[1][1] = MFMA(ga[k2][1], gb[k2][1], acc[1][1]);
;         }
;         if (kt + 1 < nk) sstore(stset, buf ^ 1, kt + 1);
; #pragma unroll
;         for (int i = 0; i < 8; ++i) { __builtin_amdgcn_sched_group_barrier(0x008, 1, 0); __builtin_amdgcn_sched_group_barrier(0x100, 1, 0); }
; #pragma unroll
;         for (int i = 0; i < 8; ++i) { __builtin_amdgcn_sched_group_barrier(0x008, 1, 0); __builtin_amdgcn_sched_group_barrier(0x200, 1, 0); }
;         __builtin_amdgcn_sched_barrier(0);
;         __syncthreads();
;     };
;     gload(R0, 0); gload(R1, 1);
;     sstore(R0, 0, 0); __syncthreads();
;     for (int kt = 0; kt < nk; kt += 2) {
;         step(kt, R0, R1);
;         if (kt + 1 < nk) step(kt + 1, R1, R0);
;     }
	v_mfma_f32_32x32x16_bf16 v[52:67], v[174:177], v[210:213], v[52:67]
	s_waitcnt lgkmcnt(1)
	v_mfma_f32_32x32x16_bf16 v[36:51], v[174:177], v[218:221], v[36:51]
	v_mfma_f32_32x32x16_bf16 v[4:19], v[202:205], v[218:221], v[4:19]
	s_waitcnt lgkmcnt(0)
	v_mfma_f32_32x32x16_bf16 v[36:51], v[178:181], v[222:225], v[36:51]
	v_mfma_f32_32x32x16_bf16 v[4:19], v[206:209], v[222:225], v[4:19]
	ds_read_b128 v[222:225], v197 offset:41568
	ds_read_b128 v[174:177], v196 offset:4672
	v_mfma_f32_32x32x16_bf16 v[20:35], v[202:205], v[210:213], v[20:35]
	ds_read_b128 v[210:213], v196 offset:4704
	ds_read_b128 v[202:205], v196 offset:64
	v_mfma_f32_32x32x16_bf16 v[52:67], v[178:181], v[214:217], v[52:67]
	ds_read_b128 v[218:221], v197 offset:36960
	ds_read_b128 v[178:181], v197 offset:41536
	v_mfma_f32_32x32x16_bf16 v[20:35], v[206:209], v[214:217], v[20:35]
	ds_read_b128 v[214:217], v197 offset:36928
	ds_read_b128 v[206:209], v196 offset:96
	s_waitcnt lgkmcnt(1)
	v_mfma_f32_32x32x16_bf16 v[52:67], v[202:205], v[214:217], v[52:67]
	s_waitcnt vmcnt(15)
	ds_write_b128 v198, v[68:71]
	v_mfma_f32_32x32x16_bf16 v[36:51], v[202:205], v[178:181], v[36:51]
	s_waitcnt vmcnt(14)
	ds_write_b128 v198, v[72:75] offset:36864
	v_mfma_f32_32x32x16_bf16 v[20:35], v[174:177], v[214:217], v[20:35]
	s_waitcnt vmcnt(13)
	ds_write_b128 v199, v[76:79]
	v_mfma_f32_32x32x16_bf16 v[4:19], v[174:177], v[178:181], v[4:19]
	s_waitcnt vmcnt(12)
	ds_write_b128 v199, v[80:83] offset:36864
	s_waitcnt lgkmcnt(4)
	v_mfma_f32_32x32x16_bf16 v[52:67], v[206:209], v[218:221], v[52:67]
	s_waitcnt vmcnt(11)
	ds_write_b128 v200, v[84:87]
	v_mfma_f32_32x32x16_bf16 v[36:51], v[206:209], v[222:225], v[36:51]
	s_waitcnt vmcnt(10)
	ds_write_b128 v200, v[92:95] offset:36864
	v_mfma_f32_32x32x16_bf16 v[20:35], v[210:213], v[218:221], v[20:35]
	s_waitcnt vmcnt(9)
	ds_write_b128 v201, v[104:107]
	v_mfma_f32_32x32x16_bf16 v[4:19], v[210:213], v[222:225], v[4:19]
	s_waitcnt vmcnt(8)
	ds_write_b128 v201, v[112:115] offset:36864
	s_branch .LBB0_55
.LBB0_58:
	ds_read_b128 v[174:177], v194
	ds_read_b128 v[178:181], v194 offset:32
	ds_read_b128 v[202:205], v194 offset:4608
	ds_read_b128 v[206:209], v194 offset:4640
	ds_read_b128 v[210:213], v195 offset:36864
	ds_read_b128 v[214:217], v195 offset:36896
	ds_read_b128 v[218:221], v195 offset:41472
	ds_read_b128 v[222:225], v195 offset:41504
	s_waitcnt lgkmcnt(3)
	v_mfma_f32_32x32x16_bf16 v[52:67], v[174:177], v[210:213], v[52:67]
	s_waitcnt lgkmcnt(1)
	v_mfma_f32_32x32x16_bf16 v[36:51], v[174:177], v[218:221], v[36:51]
	v_mfma_f32_32x32x16_bf16 v[4:19], v[202:205], v[218:221], v[4:19]
	s_waitcnt lgkmcnt(0)
	v_mfma_f32_32x32x16_bf16 v[36:51], v[178:181], v[222:225], v[36:51]
	v_mfma_f32_32x32x16_bf16 v[4:19], v[206:209], v[222:225], v[4:19]
	ds_read_b128 v[222:225], v195 offset:41568
	ds_read_b128 v[174:177], v194 offset:4672
	v_mfma_f32_32x32x16_bf16 v[20:35], v[202:205], v[210:213], v[20:35]
	ds_read_b128 v[210:213], v194 offset:4704
	ds_read_b128 v[202:205], v194 offset:64
	v_mfma_f32_32x32x16_bf16 v[52:67], v[178:181], v[214:217], v[52:67]
	ds_read_b128 v[218:221], v195 offset:36960
	ds_read_b128 v[178:181], v195 offset:41536
	v_mfma_f32_32x32x16_bf16 v[20:35], v[206:209], v[214:217], v[20:35]
	ds_read_b128 v[214:217], v195 offset:36928
	ds_read_b128 v[206:209], v194 offset:96
	s_waitcnt lgkmcnt(1)
	v_mfma_f32_32x32x16_bf16 v[52:67], v[202:205], v[214:217], v[52:67]
	s_waitcnt vmcnt(7)
	ds_write_b128 v167, v[88:91] offset:18432
	v_mfma_f32_32x32x16_bf16 v[36:51], v[202:205], v[178:181], v[36:51]
	s_waitcnt vmcnt(6)
	ds_write_b128 v167, v[96:99] offset:55296
	v_mfma_f32_32x32x16_bf16 v[20:35], v[174:177], v[214:217], v[20:35]
	s_waitcnt vmcnt(5)
	ds_write_b128 v190, v[100:103] offset:18432
	v_mfma_f32_32x32x16_bf16 v[4:19], v[174:177], v[178:181], v[4:19]
	s_waitcnt vmcnt(4)
	ds_write_b128 v190, v[108:111] offset:55296
	s_waitcnt lgkmcnt(4)
	v_mfma_f32_32x32x16_bf16 v[52:67], v[206:209], v[218:221], v[52:67]
	s_waitcnt vmcnt(3)
	ds_write_b128 v191, v[116:119] offset:18432
	v_mfma_f32_32x32x16_bf16 v[36:51], v[206:209], v[222:225], v[36:51]
	s_waitcnt vmcnt(2)
	ds_write_b128 v191, v[120:123] offset:55296
	v_mfma_f32_32x32x16_bf16 v[20:35], v[210:213], v[218:221], v[20:35]
	s_waitcnt vmcnt(1)
	ds_write_b128 v192, v[124:127] offset:18432
	v_mfma_f32_32x32x16_bf16 v[4:19], v[210:213], v[222:225], v[4:19]
	s_waitcnt vmcnt(0)
	ds_write_b128 v192, v[128:131] offset:55296
	s_waitcnt lgkmcnt(0)
	s_barrier
	ds_read_b128 v[152:155], v196
	ds_read_b128 v[156:159], v196 offset:32
	ds_read_b128 v[160:163], v196 offset:4608
	ds_read_b128 v[174:177], v196 offset:4640
	ds_read_b128 v[178:181], v197 offset:36864
	ds_read_b128 v[202:205], v197 offset:36896
	ds_read_b128 v[206:209], v197 offset:41472
	ds_read_b128 v[210:213], v197 offset:41504
	s_waitcnt lgkmcnt(3)
	v_mfma_f32_32x32x16_bf16 v[52:67], v[152:155], v[178:181], v[52:67]
	s_waitcnt lgkmcnt(1)
	v_mfma_f32_32x32x16_bf16 v[36:51], v[152:155], v[206:209], v[36:51]
	v_mfma_f32_32x32x16_bf16 v[20:35], v[160:163], v[178:181], v[20:35]
	v_mfma_f32_32x32x16_bf16 v[4:19], v[160:163], v[206:209], v[4:19]
	v_mfma_f32_32x32x16_bf16 v[52:67], v[156:159], v[202:205], v[52:67]
	s_waitcnt lgkmcnt(0)
	v_mfma_f32_32x32x16_bf16 v[36:51], v[156:159], v[210:213], v[36:51]
	v_mfma_f32_32x32x16_bf16 v[20:35], v[174:177], v[202:205], v[20:35]
	v_mfma_f32_32x32x16_bf16 v[4:19], v[174:177], v[210:213], v[4:19]
	ds_read_b128 v[152:155], v196 offset:64
	ds_read_b128 v[156:159], v197 offset:36928
	ds_read_b128 v[160:163], v196 offset:96
	ds_read_b128 v[174:177], v197 offset:36960
	ds_read_b128 v[178:181], v197 offset:41536
	ds_read_b128 v[202:205], v197 offset:41568
	s_waitcnt lgkmcnt(4)
	v_mfma_f32_32x32x16_bf16 v[52:67], v[152:155], v[156:159], v[52:67]
	s_waitcnt lgkmcnt(1)
	v_mfma_f32_32x32x16_bf16 v[36:51], v[152:155], v[178:181], v[36:51]
	ds_read_b128 v[152:155], v196 offset:4672
	ds_read_b128 v[206:209], v196 offset:4704
	s_waitcnt lgkmcnt(1)
	v_mfma_f32_32x32x16_bf16 v[20:35], v[152:155], v[156:159], v[20:35]
	v_mfma_f32_32x32x16_bf16 v[4:19], v[152:155], v[178:181], v[4:19]
	v_mfma_f32_32x32x16_bf16 v[52:67], v[160:163], v[174:177], v[52:67]
	v_mfma_f32_32x32x16_bf16 v[36:51], v[160:163], v[202:205], v[36:51]
	s_waitcnt lgkmcnt(0)
	v_mfma_f32_32x32x16_bf16 v[20:35], v[206:209], v[174:177], v[20:35]
	v_mfma_f32_32x32x16_bf16 v[4:19], v[206:209], v[202:205], v[4:19]
	s_branch .LBB0_55

; #define MFMA(a, b, c) __builtin_amdgcn_mfma_f32_32x32x16_bf16((a), (b), (c), 0, 0, 0)
; template <class Epi, class ColV>
; DI void gemm_tile(const bf16_t* __restrict__ A, int lda, const bf16_t* __restrict__ Bt, int ldb, int K, int m0, int n0, unsigned char* smem, Epi epi, ColV colv, const bf16_t* __restrict__ HYT = nullptr) {
;     ...
;     auto gload = [&](u32x4 (&r)[8], int kt) {
; #pragma unroll
;         for (int i = 0; i < 4; ++i) { int id = tid + 256 * i, row = id >> 3, kc = id & 7;
;             if (HYT && kt >= 12) r[i] = *(const u32x4*)(HYT + (size_t)((kt - 12) * 64 + (id >> 4)) * NT + m0 + (id & 15) * 8);
;             else r[i] = *(const u32x4*)(A + (size_t)(m0 + row) * lda + kt * 64 + kc * 8);
;             r[4 + i] = *(const u32x4*)(Bt + (size_t)(n0 + row) * ldb + kt * 64 + kc * 8); }
;     };
;     auto sstore = [&](const u32x4 (&r)[8], int buf, int kt) {
; #pragma unroll
;         for (int i = 0; i < 4; ++i) { int id = tid + 256 * i, row = id >> 3, kc = id & 7;
;             if (HYT && kt >= 12) { const int kk = id >> 4, rr = (id & 15) * 8; bf16_t* d = As + (buf * 128 + rr) * LS + kk; const bf16x8 v = __builtin_bit_cast(bf16x8, r[i]);
; #pragma unroll
;                 for (int e = 0; e < 8; ++e) d[e * LS] = (bf16_t)v[e]; }
;             else *(u32x4*)(As + (buf * 128 + row) * LS + kc * 8) = r[i];
;             *(u32x4*)(Bs + (buf * 128 + row) * LS + kc * 8) = r[4 + i]; }
;     };
;     auto step = [&](int kt, u32x4 (&ldset)[8], const u32x4 (&stset)[8]) {
;         const int buf = kt & 1;
;         if (kt + 2 < nk) gload(ldset, kt + 2);
;         const bf16_t* Ab = As + (buf * 128 + 64 * wr + li) * LS + 8 * lh;
;         const bf16_t* Bb = Bs + (buf * 128 + 64 * wc + li) * LS + 8 * lh;
;         bf16x8 fa[2][2], fb[2][2], ga[2][2], gb[2][2];
; #pragma unroll
;         for (int k2 = 0; k2 < 2; ++k2) { fa[k2][0] = ld8(Ab + 16 * k2); fa[k2][1] = ld8(Ab + 32 * LS + 16 * k2); fb[k2][0] = ld8(Bb + 16 * k2); fb[k2][1] = ld8(Bb + 32 * LS + 16 * k2); }
;         __builtin_amdgcn_sched_barrier(0);
; #pragma unroll
;         for (int k2 = 0; k2 < 2; ++k2) {
;             acc[0][0] = MFMA(fa[k2][0], fb[k2][0], acc[0][0]); acc[0][1] = MFMA(fa[k2][0], fb[k2][1], acc[0][1]);
;             acc[1][0] = MFMA(fa[k2][1], fb[k2][0], acc[1][0]); acc[1][1] = MFMA(fa[k2][1], fb[k2][1], acc[1][1]);
;         }
; #pragma unroll
.LBB0_1558:
	s_cmp_lt_u32 s19, 14
	s_cselect_b64 s[12:13], -1, 0
	s_cmp_gt_u32 s19, 13
	s_cselect_b64 s[10:11], -1, 0
	s_and_b64 vcc, exec, s[10:11]
	v_lshl_add_u64 v[164:165], v[144:145], 0, v[2:3]
	v_lshl_add_u64 v[162:163], v[0:1], 0, v[2:3]
	v_lshl_add_u64 v[160:161], v[142:143], 0, v[2:3]
	v_lshl_add_u64 v[158:159], v[132:133], 0, v[2:3]
	v_lshl_add_u64 v[156:157], v[140:141], 0, v[2:3]
	v_lshl_add_u64 v[154:155], v[134:135], 0, v[2:3]
	v_lshl_add_u64 v[152:153], v[138:139], 0, v[2:3]
	v_lshl_add_u64 v[146:147], v[136:137], 0, v[2:3]
	s_cbranch_vccnz .LBB0_1560
	v_add_co_u32_e32 v68, vcc, 0x26ca000, v164
	s_nop 1
	v_addc_co_u32_e32 v69, vcc, 0, v165, vcc
	v_add_co_u32_e32 v76, vcc, 0x26ca000, v160
	global_load_dwordx4 v[68:71], v[68:69], off offset:256
	s_nop 0
	global_load_dwordx4 v[72:75], v[162:163], off offset:256
	v_addc_co_u32_e32 v77, vcc, 0, v161, vcc
	v_add_co_u32_e32 v84, vcc, 0x26ca000, v156
	global_load_dwordx4 v[76:79], v[76:77], off offset:256
	s_nop 0
	global_load_dwordx4 v[80:83], v[158:159], off offset:256
	v_addc_co_u32_e32 v85, vcc, 0, v157, vcc
	v_add_co_u32_e32 v92, vcc, 0x26ca000, v152
	global_load_dwordx4 v[84:87], v[84:85], off offset:256
	s_nop 0
	global_load_dwordx4 v[88:91], v[154:155], off offset:256
	v_addc_co_u32_e32 v93, vcc, 0, v153, vcc
	global_load_dwordx4 v[92:95], v[92:93], off offset:256
	s_nop 0
	global_load_dwordx4 v[104:107], v[146:147], off offset:256
	ds_read_b128 v[202:205], v194
	ds_read_b128 v[206:209], v194 offset:32
	ds_read_b128 v[210:213], v194 offset:4608
	ds_read_b128 v[214:217], v194 offset:4640
	ds_read_b128 v[218:221], v195 offset:36864
	ds_read_b128 v[222:225], v195 offset:36896
	ds_read_b128 v[226:229], v195 offset:41472
	ds_read_b128 v[230:233], v195 offset:41504
	s_waitcnt lgkmcnt(3)
	v_mfma_f32_32x32x16_bf16 v[52:67], v[202:205], v[218:221], v[52:67]
	s_waitcnt lgkmcnt(1)
	v_mfma_f32_32x32x16_bf16 v[36:51], v[202:205], v[226:229], v[36:51]
	v_mfma_f32_32x32x16_bf16 v[4:19], v[210:213], v[226:229], v[4:19]
	s_waitcnt lgkmcnt(0)
	v_mfma_f32_32x32x16_bf16 v[36:51], v[206:209], v[230:233], v[36:51]
	v_mfma_f32_32x32x16_bf16 v[4:19], v[214:217], v[230:233], v[4:19]
	ds_read_b128 v[230:233], v195 offset:41568
	ds_read_b128 v[202:205], v194 offset:4672
	v_mfma_f32_32x32x16_bf16 v[20:35], v[210:213], v[218:221], v[20:35]
	ds_read_b128 v[218:221], v194 offset:4704
	ds_read_b128 v[210:213], v194 offset:64
	v_mfma_f32_32x32x16_bf16 v[52:67], v[206:209], v[222:225], v[52:67]
	ds_read_b128 v[226:229], v195 offset:36960
	ds_read_b128 v[206:209], v195 offset:41536
	v_mfma_f32_32x32x16_bf16 v[20:35], v[214:217], v[222:225], v[20:35]
	ds_read_b128 v[222:225], v195 offset:36928
	ds_read_b128 v[214:217], v194 offset:96
	s_waitcnt lgkmcnt(1)
	v_mfma_f32_32x32x16_bf16 v[52:67], v[210:213], v[222:225], v[52:67]
	s_waitcnt vmcnt(15)
	ds_write_b128 v167, v[96:99] offset:18432
	v_mfma_f32_32x32x16_bf16 v[36:51], v[210:213], v[206:209], v[36:51]
	s_waitcnt vmcnt(11)
	ds_write_b128 v167, v[100:103] offset:55296
	v_mfma_f32_32x32x16_bf16 v[20:35], v[202:205], v[222:225], v[20:35]
	ds_write_b128 v190, v[108:111] offset:18432
	v_mfma_f32_32x32x16_bf16 v[4:19], v[202:205], v[206:209], v[4:19]
	s_waitcnt vmcnt(10)
	ds_write_b128 v190, v[112:115] offset:55296
	s_waitcnt lgkmcnt(4)
	v_mfma_f32_32x32x16_bf16 v[52:67], v[214:217], v[226:229], v[52:67]
	ds_write_b128 v191, v[116:119] offset:18432
	v_mfma_f32_32x32x16_bf16 v[36:51], v[214:217], v[230:233], v[36:51]
	s_waitcnt vmcnt(9)
	ds_write_b128 v191, v[120:123] offset:55296
	v_mfma_f32_32x32x16_bf16 v[20:35], v[218:221], v[226:229], v[20:35]
	ds_write_b128 v192, v[124:127] offset:18432
	v_mfma_f32_32x32x16_bf16 v[4:19], v[218:221], v[230:233], v[4:19]
	s_waitcnt vmcnt(8)
	ds_write_b128 v192, v[128:131] offset:55296
	s_waitcnt lgkmcnt(0)
	s_barrier
	v_add_co_u32_e32 v96, vcc, 0x26ca000, v164
	s_nop 1
	v_addc_co_u32_e32 v97, vcc, 0, v165, vcc
	v_add_co_u32_e32 v108, vcc, 0x26ca000, v160
	global_load_dwordx4 v[96:99], v[96:97], off offset:384
	s_nop 0
	global_load_dwordx4 v[100:103], v[162:163], off offset:384
	v_addc_co_u32_e32 v109, vcc, 0, v161, vcc
	v_add_co_u32_e32 v116, vcc, 0x26ca000, v156
	global_load_dwordx4 v[108:111], v[108:109], off offset:384
	s_nop 0
	global_load_dwordx4 v[112:115], v[158:159], off offset:384
	v_addc_co_u32_e32 v117, vcc, 0, v157, vcc
	v_add_co_u32_e32 v124, vcc, 0x26ca000, v152
	global_load_dwordx4 v[116:119], v[116:117], off offset:384
	s_nop 0
	global_load_dwordx4 v[120:123], v[154:155], off offset:384
	v_addc_co_u32_e32 v125, vcc, 0, v153, vcc
	global_load_dwordx4 v[124:127], v[124:125], off offset:384
	s_nop 0
	global_load_dwordx4 v[128:131], v[146:147], off offset:384
	ds_read_b128 v[202:205], v196
	ds_read_b128 v[206:209], v196 offset:32
	ds_read_b128 v[210:213], v196 offset:4608
	ds_read_b128 v[214:217], v196 offset:4640
	ds_read_b128 v[218:221], v197 offset:36864
	ds_read_b128 v[222:225], v197 offset:36896
	ds_read_b128 v[226:229], v197 offset:41472
	ds_read_b128 v[230:233], v197 offset:41504
	s_waitcnt lgkmcnt(3)
	v_mfma_f32_32x32x16_bf16 v[52:67], v[202:205], v[218:221], v[52:67]
	s_waitcnt lgkmcnt(1)
	v_mfma_f32_32x32x16_bf16 v[36:51], v[202:205], v[226:229], v[36:51]
	v_mfma_f32_32x32x16_bf16 v[4:19], v[210:213], v[226:229], v[4:19]
	s_waitcnt lgkmcnt(0)
	v_mfma_f32_32x32x16_bf16 v[36:51], v[206:209], v[230:233], v[36:51]
	v_mfma_f32_32x32x16_bf16 v[4:19], v[214:217], v[230:233], v[4:19]
	ds_read_b128 v[230:233], v197 offset:41568
	ds_read_b128 v[202:205], v196 offset:4672
	v_mfma_f32_32x32x16_bf16 v[20:35], v[210:213], v[218:221], v[20:35]
	ds_read_b128 v[218:221], v196 offset:4704
	ds_read_b128 v[210:213], v196 offset:64
	v_mfma_f32_32x32x16_bf16 v[52:67], v[206:209], v[222:225], v[52:67]
	ds_read_b128 v[226:229], v197 offset:36960
	ds_read_b128 v[206:209], v197 offset:41536
	v_mfma_f32_32x32x16_bf16 v[20:35], v[214:217], v[222:225], v[20:35]
	ds_read_b128 v[222:225], v197 offset:36928
	ds_read_b128 v[214:217], v196 offset:96
	s_waitcnt lgkmcnt(1)
	v_mfma_f32_32x32x16_bf16 v[52:67], v[210:213], v[222:225], v[52:67]
	s_waitcnt vmcnt(15)
	ds_write_b128 v198, v[68:71]
	v_mfma_f32_32x32x16_bf16 v[36:51], v[210:213], v[206:209], v[36:51]
	s_waitcnt vmcnt(14)
	ds_write_b128 v198, v[72:75] offset:36864
	v_mfma_f32_32x32x16_bf16 v[20:35], v[202:205], v[222:225], v[20:35]
	s_waitcnt vmcnt(13)
	ds_write_b128 v199, v[76:79]
	v_mfma_f32_32x32x16_bf16 v[4:19], v[202:205], v[206:209], v[4:19]
	s_waitcnt vmcnt(12)
	ds_write_b128 v199, v[80:83] offset:36864
	s_waitcnt lgkmcnt(4)
	v_mfma_f32_32x32x16_bf16 v[52:67], v[214:217], v[226:229], v[52:67]
	s_waitcnt vmcnt(11)
	ds_write_b128 v200, v[84:87]
	v_mfma_f32_32x32x16_bf16 v[36:51], v[214:217], v[230:233], v[36:51]
	s_waitcnt vmcnt(10)
	ds_write_b128 v200, v[88:91] offset:36864
	v_mfma_f32_32x32x16_bf16 v[20:35], v[218:221], v[226:229], v[20:35]
	s_waitcnt vmcnt(9)
	ds_write_b128 v201, v[92:95]
	v_mfma_f32_32x32x16_bf16 v[4:19], v[218:221], v[230:233], v[4:19]
	s_waitcnt vmcnt(8)
	ds_write_b128 v201, v[104:107] offset:36864
	s_branch .LBB0_1557
; template <class Epi, class ColV>
; DI void gemm_tile(const bf16_t* __restrict__ A, int lda, const bf16_t* __restrict__ Bt, int ldb, int K, int m0, int n0, unsigned char* smem, Epi epi, ColV colv, const bf16_t* __restrict__ HYT = nullptr) {
;     ...
;     auto step = [&](int kt, u32x4 (&ldset)[8], const u32x4 (&stset)[8]) {
;         const int buf = kt & 1;
;         if (kt + 2 < nk) gload(ldset, kt + 2);
;         const bf16_t* Ab = As + (buf * 128 + 64 * wr + li) * LS + 8 * lh;
;         const bf16_t* Bb = Bs + (buf * 128 + 64 * wc + li) * LS + 8 * lh;
;         bf16x8 fa[2][2], fb[2][2], ga[2][2], gb[2][2];
; #pragma unroll
;         for (int k2 = 0; k2 < 2; ++k2) { fa[k2][0] = ld8(Ab + 16 * k2); fa[k2][1] = ld8(Ab + 32 * LS + 16 * k2); fb[k2][0] = ld8(Bb + 16 * k2); fb[k2][1] = ld8(Bb + 32 * LS + 16 * k2); }
;         __builtin_amdgcn_sched_barrier(0);
; #pragma unroll
;         for (int k2 = 0; k2 < 2; ++k2) {
;             acc[0][0] = MFMA(fa[k2][0], fb[k2][0], acc[0][0]); acc[0][1] = MFMA(fa[k2][0], fb[k2][1], acc[0][1]);
;             acc[1][0] = MFMA(fa[k2][1], fb[k2][0], acc[1][0]); acc[1][1] = MFMA(fa[k2][1], fb[k2][1], acc[1][1]);
;         }
; #pragma unroll
;         for (int k2 = 0; k2 < 2; ++k2) { const int ks = 2 + k2; ga[k2][0] = ld8(Ab + 16 * ks); ga[k2][1] = ld8(Ab + 32 * LS + 16 * ks); gb[k2][0] = ld8(Bb + 16 * ks); gb[k2][1] = ld8(Bb + 32 * LS + 16 * ks); }
; #pragma unroll
;         for (int k2 = 0; k2 < 2; ++k2) {
;             acc[0][0] = MFMA(ga[k2][0], gb[k2][0], acc[0][0]); acc[0][1] = MFMA(ga[k2][0], gb[k2][1], acc[0][1]);
;             acc[1][0] = MFMA(ga[k2][1], gb[k2][0], acc[1][0]); acc[1][1] = MFMA(ga[k2][1], gb[k2][1], acc[1][1]);
;         }
;         if (kt + 1 < nk) sstore(stset, buf ^ 1, kt + 1);
; #pragma unroll
;         for (int i = 0; i < 8; ++i) { __builtin_amdgcn_sched_group_barrier(0x008, 1, 0); __builtin_amdgcn_sched_group_barrier(0x100, 1, 0); }
; #pragma unroll
;         for (int i = 0; i < 8; ++i) { __builtin_amdgcn_sched_group_barrier(0x008, 1, 0); __builtin_amdgcn_sched_group_barrier(0x200, 1, 0); }
;         __builtin_amdgcn_sched_barrier(0);
;         __syncthreads();
;     };
;     gload(R0, 0); gload(R1, 1);
;     sstore(R0, 0, 0); __syncthreads();
;     for (int kt = 0; kt < nk; kt += 2) {
;         step(kt, R0, R1);
;         if (kt + 1 < nk) step(kt + 1, R1, R0);
;     }
.LBB0_1560:
	ds_read_b128 v[202:205], v194
	ds_read_b128 v[206:209], v194 offset:32
	ds_read_b128 v[210:213], v194 offset:4608
	ds_read_b128 v[214:217], v194 offset:4640
	ds_read_b128 v[218:221], v195 offset:36864
	ds_read_b128 v[222:225], v195 offset:36896
	ds_read_b128 v[226:229], v195 offset:41472
	ds_read_b128 v[230:233], v195 offset:41504
	s_waitcnt lgkmcnt(3)
	v_mfma_f32_32x32x16_bf16 v[52:67], v[202:205], v[218:221], v[52:67]
	s_waitcnt lgkmcnt(1)
	v_mfma_f32_32x32x16_bf16 v[36:51], v[202:205], v[226:229], v[36:51]
	v_mfma_f32_32x32x16_bf16 v[4:19], v[210:213], v[226:229], v[4:19]
	s_waitcnt lgkmcnt(0)
	v_mfma_f32_32x32x16_bf16 v[36:51], v[206:209], v[230:233], v[36:51]
	v_mfma_f32_32x32x16_bf16 v[4:19], v[214:217], v[230:233], v[4:19]
	ds_read_b128 v[230:233], v195 offset:41568
	ds_read_b128 v[202:205], v194 offset:4672
	v_mfma_f32_32x32x16_bf16 v[20:35], v[210:213], v[218:221], v[20:35]
	ds_read_b128 v[218:221], v194 offset:4704
	ds_read_b128 v[210:213], v194 offset:64
	v_mfma_f32_32x32x16_bf16 v[52:67], v[206:209], v[222:225], v[52:67]
	ds_read_b128 v[226:229], v195 offset:36960
	ds_read_b128 v[206:209], v195 offset:41536
	v_mfma_f32_32x32x16_bf16 v[20:35], v[214:217], v[222:225], v[20:35]
	ds_read_b128 v[222:225], v195 offset:36928
	ds_read_b128 v[214:217], v194 offset:96
	s_waitcnt lgkmcnt(1)
	v_mfma_f32_32x32x16_bf16 v[52:67], v[210:213], v[222:225], v[52:67]
	s_waitcnt vmcnt(7)
	ds_write_b128 v167, v[96:99] offset:18432
	v_mfma_f32_32x32x16_bf16 v[36:51], v[210:213], v[206:209], v[36:51]
	s_waitcnt vmcnt(3)
	ds_write_b128 v167, v[100:103] offset:55296
	v_mfma_f32_32x32x16_bf16 v[20:35], v[202:205], v[222:225], v[20:35]
	ds_write_b128 v190, v[108:111] offset:18432
	v_mfma_f32_32x32x16_bf16 v[4:19], v[202:205], v[206:209], v[4:19]
	s_waitcnt vmcnt(2)
	ds_write_b128 v190, v[112:115] offset:55296
	s_waitcnt lgkmcnt(4)
	v_mfma_f32_32x32x16_bf16 v[52:67], v[214:217], v[226:229], v[52:67]
	ds_write_b128 v191, v[116:119] offset:18432
	v_mfma_f32_32x32x16_bf16 v[36:51], v[214:217], v[230:233], v[36:51]
	s_waitcnt vmcnt(1)
	ds_write_b128 v191, v[120:123] offset:55296
	v_mfma_f32_32x32x16_bf16 v[20:35], v[218:221], v[226:229], v[20:35]
	ds_write_b128 v192, v[124:127] offset:18432
	v_mfma_f32_32x32x16_bf16 v[4:19], v[218:221], v[230:233], v[4:19]
	s_waitcnt vmcnt(0)
	ds_write_b128 v192, v[128:131] offset:55296
	s_waitcnt lgkmcnt(0)
	s_barrier
	ds_read_b128 v[152:155], v196
	ds_read_b128 v[156:159], v196 offset:32
	ds_read_b128 v[160:163], v196 offset:4608
	ds_read_b128 v[202:205], v196 offset:4640
	ds_read_b128 v[206:209], v197 offset:36864
	ds_read_b128 v[210:213], v197 offset:36896
	ds_read_b128 v[214:217], v197 offset:41472
	ds_read_b128 v[218:221], v197 offset:41504
	s_waitcnt lgkmcnt(3)
	v_mfma_f32_32x32x16_bf16 v[52:67], v[152:155], v[206:209], v[52:67]
	s_waitcnt lgkmcnt(1)
	v_mfma_f32_32x32x16_bf16 v[36:51], v[152:155], v[214:217], v[36:51]
	v_mfma_f32_32x32x16_bf16 v[20:35], v[160:163], v[206:209], v[20:35]
	v_mfma_f32_32x32x16_bf16 v[4:19], v[160:163], v[214:217], v[4:19]
	v_mfma_f32_32x32x16_bf16 v[52:67], v[156:159], v[210:213], v[52:67]
	s_waitcnt lgkmcnt(0)
	v_mfma_f32_32x32x16_bf16 v[36:51], v[156:159], v[218:221], v[36:51]
	v_mfma_f32_32x32x16_bf16 v[20:35], v[202:205], v[210:213], v[20:35]
	v_mfma_f32_32x32x16_bf16 v[4:19], v[202:205], v[218:221], v[4:19]
	ds_read_b128 v[152:155], v196 offset:64
	ds_read_b128 v[156:159], v197 offset:36928
	ds_read_b128 v[160:163], v196 offset:96
	ds_read_b128 v[202:205], v197 offset:36960
	ds_read_b128 v[206:209], v197 offset:41536
	ds_read_b128 v[210:213], v197 offset:41568
	s_waitcnt lgkmcnt(4)
	v_mfma_f32_32x32x16_bf16 v[52:67], v[152:155], v[156:159], v[52:67]
	s_waitcnt lgkmcnt(1)
	v_mfma_f32_32x32x16_bf16 v[36:51], v[152:155], v[206:209], v[36:51]
	ds_read_b128 v[152:155], v196 offset:4672
	ds_read_b128 v[214:217], v196 offset:4704
	s_waitcnt lgkmcnt(1)
	v_mfma_f32_32x32x16_bf16 v[20:35], v[152:155], v[156:159], v[20:35]
	v_mfma_f32_32x32x16_bf16 v[4:19], v[152:155], v[206:209], v[4:19]
	v_mfma_f32_32x32x16_bf16 v[52:67], v[160:163], v[202:205], v[52:67]
	v_mfma_f32_32x32x16_bf16 v[36:51], v[160:163], v[210:213], v[36:51]
	s_waitcnt lgkmcnt(0)
	v_mfma_f32_32x32x16_bf16 v[20:35], v[214:217], v[202:205], v[20:35]
	v_mfma_f32_32x32x16_bf16 v[4:19], v[214:217], v[210:213], v[4:19]
	s_branch .LBB0_1557
